# in-projection wide-tile mainloops: operands via LDS-DMA into a 3-stage swizzled LDS ring, two K steps in flight, one barrier per step (no staging registers)
# speedup vs baseline: 1.0542x; 1.0116x over previous
.LBB0_263:
	v_and_b32_e32 v209, 31, v213
	v_bfe_u32 v211, v213, 5, 1
	v_bfe_u32 v210, v213, 6, 1
	v_ashrrev_i32_e32 v212, 7, v213
	s_andn2_b64 vcc, exec, s[6:7]
	v_lshl_add_u64 v[170:171], v[168:169], 0, s[0:1]
	v_lshl_add_u64 v[172:173], v[168:169], 0, s[82:83]
	v_lshlrev_b32_e32 v176, 1, v164
	v_lshlrev_b32_e32 v174, 1, v162
	s_cbranch_vccnz .LBB0_311
	v_lshrrev_b32_e32 v128, 2, v204
	v_lshrrev_b32_e32 v129, 4, v204
	v_xor_b32_e32 v129, v129, v204
	v_and_b32_e32 v129, 3, v129
	v_lshlrev_b32_e32 v129, 4, v129
	v_lshl_or_b32 v128, v128, 11, v129
	v_add_u32_e32 v129, 0x20000, v128
	v_add_u32_e32 v130, 0x40000, v128
	v_add_u32_e32 v131, 0x60000, v128
	v_bfe_u32 v132, v209, 2, 2
	v_xor_b32_e32 v132, v132, v211
	v_lshlrev_b32_e32 v132, 4, v132
	v_lshl_or_b32 v132, v209, 6, v132
	v_lshl_or_b32 v133, v210, 12, v132
	v_xor_b32_e32 v134, 32, v133
	v_lshl_or_b32 v135, v212, 13, v132
	v_add_u32_e32 v135, 0x2000, v135
	v_xor_b32_e32 v136, 32, v135
	v_lshrrev_b32_e32 v137, 6, v204
	v_lshlrev_b32_e32 v137, 10, v137
	s_nop 1
	v_readfirstlane_b32 vcc_lo, v137
	s_mov_b64 s[0:1], s[78:79]
	s_mov_b64 s[6:7], s[80:81]
	s_mov_b32 s4, 0
	s_mov_b32 s5, 0
	s_mov_b32 m0, vcc_lo
	s_nop 0
	global_load_lds_dwordx4 v128, s[0:1]
	s_add_u32 m0, m0, 0x1000
	s_nop 0
	global_load_lds_dwordx4 v129, s[0:1]
	s_add_u32 m0, m0, 0x1000
	s_nop 0
	global_load_lds_dwordx4 v128, s[6:7]
	s_add_u32 m0, m0, 0x1000
	s_nop 0
	global_load_lds_dwordx4 v129, s[6:7]
	s_add_u32 m0, m0, 0x1000
	s_nop 0
	global_load_lds_dwordx4 v130, s[6:7]
	s_add_u32 m0, m0, 0x1000
	s_nop 0
	global_load_lds_dwordx4 v131, s[6:7]
	s_add_u32 s0, s0, 64
	s_addc_u32 s1, s1, 0
	s_add_u32 s6, s6, 64
	s_addc_u32 s7, s7, 0
	s_add_u32 m0, vcc_lo, 0x6000
	s_nop 0
	global_load_lds_dwordx4 v128, s[0:1]
	s_add_u32 m0, m0, 0x1000
	s_nop 0
	global_load_lds_dwordx4 v129, s[0:1]
	s_add_u32 m0, m0, 0x1000
	s_nop 0
	global_load_lds_dwordx4 v128, s[6:7]
	s_add_u32 m0, m0, 0x1000
	s_nop 0
	global_load_lds_dwordx4 v129, s[6:7]
	s_add_u32 m0, m0, 0x1000
	s_nop 0
	global_load_lds_dwordx4 v130, s[6:7]
	s_add_u32 m0, m0, 0x1000
	s_nop 0
	global_load_lds_dwordx4 v131, s[6:7]
	s_add_u32 s0, s0, 64
	s_addc_u32 s1, s1, 0
	s_add_u32 s6, s6, 64
	s_addc_u32 s7, s7, 0
	v_mov_b32_e32 v0, 0
	v_mov_b32_e32 v1, 0
	v_mov_b32_e32 v2, 0
	v_mov_b32_e32 v3, 0
	v_mov_b32_e32 v4, 0
	v_mov_b32_e32 v5, 0
	v_mov_b32_e32 v6, 0
	v_mov_b32_e32 v7, 0
	v_mov_b32_e32 v8, 0
	v_mov_b32_e32 v9, 0
	v_mov_b32_e32 v10, 0
	v_mov_b32_e32 v11, 0
	v_mov_b32_e32 v12, 0
	v_mov_b32_e32 v13, 0
	v_mov_b32_e32 v14, 0
	v_mov_b32_e32 v15, 0
	v_mov_b32_e32 v16, 0
	v_mov_b32_e32 v17, 0
	v_mov_b32_e32 v18, 0
	v_mov_b32_e32 v19, 0
	v_mov_b32_e32 v20, 0
	v_mov_b32_e32 v21, 0
	v_mov_b32_e32 v22, 0
	v_mov_b32_e32 v23, 0
	v_mov_b32_e32 v24, 0
	v_mov_b32_e32 v25, 0
	v_mov_b32_e32 v26, 0
	v_mov_b32_e32 v27, 0
	v_mov_b32_e32 v28, 0
	v_mov_b32_e32 v29, 0
	v_mov_b32_e32 v30, 0
	v_mov_b32_e32 v31, 0
	v_mov_b32_e32 v32, 0
	v_mov_b32_e32 v33, 0
	v_mov_b32_e32 v34, 0
	v_mov_b32_e32 v35, 0
	v_mov_b32_e32 v36, 0
	v_mov_b32_e32 v37, 0
	v_mov_b32_e32 v38, 0
	v_mov_b32_e32 v39, 0
	v_mov_b32_e32 v40, 0
	v_mov_b32_e32 v41, 0
	v_mov_b32_e32 v42, 0
	v_mov_b32_e32 v43, 0
	v_mov_b32_e32 v44, 0
	v_mov_b32_e32 v45, 0
	v_mov_b32_e32 v46, 0
	v_mov_b32_e32 v47, 0
	v_mov_b32_e32 v48, 0
	v_mov_b32_e32 v49, 0
	v_mov_b32_e32 v50, 0
	v_mov_b32_e32 v51, 0
	v_mov_b32_e32 v52, 0
	v_mov_b32_e32 v53, 0
	v_mov_b32_e32 v54, 0
	v_mov_b32_e32 v55, 0
	v_mov_b32_e32 v56, 0
	v_mov_b32_e32 v57, 0
	v_mov_b32_e32 v58, 0
	v_mov_b32_e32 v59, 0
	v_mov_b32_e32 v60, 0
	v_mov_b32_e32 v61, 0
	v_mov_b32_e32 v62, 0
	v_mov_b32_e32 v63, 0
	v_mov_b32_e32 v64, 0
	v_mov_b32_e32 v65, 0
	v_mov_b32_e32 v66, 0
	v_mov_b32_e32 v67, 0
	v_mov_b32_e32 v68, 0
	v_mov_b32_e32 v69, 0
	v_mov_b32_e32 v70, 0
	v_mov_b32_e32 v71, 0
	v_mov_b32_e32 v72, 0
	v_mov_b32_e32 v73, 0
	v_mov_b32_e32 v74, 0
	v_mov_b32_e32 v75, 0
	v_mov_b32_e32 v76, 0
	v_mov_b32_e32 v77, 0
	v_mov_b32_e32 v78, 0
	v_mov_b32_e32 v79, 0
	v_mov_b32_e32 v80, 0
	v_mov_b32_e32 v81, 0
	v_mov_b32_e32 v82, 0
	v_mov_b32_e32 v83, 0
	v_mov_b32_e32 v84, 0
	v_mov_b32_e32 v85, 0
	v_mov_b32_e32 v86, 0
	v_mov_b32_e32 v87, 0
	v_mov_b32_e32 v88, 0
	v_mov_b32_e32 v89, 0
	v_mov_b32_e32 v90, 0
	v_mov_b32_e32 v91, 0
	v_mov_b32_e32 v92, 0
	v_mov_b32_e32 v93, 0
	v_mov_b32_e32 v94, 0
	v_mov_b32_e32 v95, 0
	v_mov_b32_e32 v96, 0
	v_mov_b32_e32 v97, 0
	v_mov_b32_e32 v98, 0
	v_mov_b32_e32 v99, 0
	v_mov_b32_e32 v100, 0
	v_mov_b32_e32 v101, 0
	v_mov_b32_e32 v102, 0
	v_mov_b32_e32 v103, 0
	v_mov_b32_e32 v104, 0
	v_mov_b32_e32 v105, 0
	v_mov_b32_e32 v106, 0
	v_mov_b32_e32 v107, 0
	v_mov_b32_e32 v108, 0
	v_mov_b32_e32 v109, 0
	v_mov_b32_e32 v110, 0
	v_mov_b32_e32 v111, 0
	v_mov_b32_e32 v112, 0
	v_mov_b32_e32 v113, 0
	v_mov_b32_e32 v114, 0
	v_mov_b32_e32 v115, 0
	v_mov_b32_e32 v116, 0
	v_mov_b32_e32 v117, 0
	v_mov_b32_e32 v118, 0
	v_mov_b32_e32 v119, 0
	v_mov_b32_e32 v120, 0
	v_mov_b32_e32 v121, 0
	v_mov_b32_e32 v122, 0
	v_mov_b32_e32 v123, 0
	v_mov_b32_e32 v124, 0
	v_mov_b32_e32 v125, 0
	v_mov_b32_e32 v126, 0
	v_mov_b32_e32 v127, 0
.Lp2a_top:
	s_cmp_eq_u32 s4, 31
	s_cbranch_scc1 .Lp2a_w0
	s_waitcnt vmcnt(6)
	s_branch .Lp2a_bar

.Lp2a_bar:
	s_barrier
	s_cmp_gt_u32 s4, 29
	s_cbranch_scc1 .Lp2a_comp
	s_add_u32 vcc_hi, s5, 0xc000
	s_sub_u32 m0, vcc_hi, 0x12000
	s_cmp_lt_u32 s5, 0x6000
	s_cselect_b32 vcc_hi, vcc_hi, m0
	s_add_u32 m0, vcc_hi, vcc_lo
	s_nop 0
	global_load_lds_dwordx4 v128, s[0:1]
	s_add_u32 m0, m0, 0x1000
	s_nop 0
	global_load_lds_dwordx4 v129, s[0:1]
	s_add_u32 m0, m0, 0x1000
	s_nop 0
	global_load_lds_dwordx4 v128, s[6:7]
	s_add_u32 m0, m0, 0x1000
	s_nop 0
	global_load_lds_dwordx4 v129, s[6:7]
	s_add_u32 m0, m0, 0x1000
	s_nop 0
	global_load_lds_dwordx4 v130, s[6:7]
	s_add_u32 m0, m0, 0x1000
	s_nop 0
	global_load_lds_dwordx4 v131, s[6:7]
	s_add_u32 s0, s0, 64
	s_addc_u32 s1, s1, 0
	s_add_u32 s6, s6, 64
	s_addc_u32 s7, s7, 0
.Lp2a_comp:
	v_add_u32_e32 v137, s5, v133
	v_add_u32_e32 v138, s5, v134
	v_add_u32_e32 v139, s5, v135
	v_add_u32_e32 v140, s5, v136
	ds_read_b128 v[214:217], v139
	ds_read_b128 v[218:221], v137
	ds_read_b128 v[222:225], v138
	ds_read_b128 v[226:229], v140
	ds_read_b128 v[230:233], v137 offset:2048
	ds_read_b128 v[234:237], v138 offset:2048
	s_waitcnt lgkmcnt(4)
	v_mfma_f32_32x32x16_bf16 v[112:127], v[214:217], v[218:221], v[112:127]
	s_waitcnt lgkmcnt(1)
	v_mfma_f32_32x32x16_bf16 v[48:63], v[214:217], v[230:233], v[48:63]
	ds_read_b128 v[214:217], v139 offset:2048
	ds_read_b128 v[238:241], v140 offset:2048
	s_waitcnt lgkmcnt(1)
	v_mfma_f32_32x32x16_bf16 v[96:111], v[214:217], v[218:221], v[96:111]
	v_mfma_f32_32x32x16_bf16 v[32:47], v[214:217], v[230:233], v[32:47]
	ds_read_b128 v[214:217], v139 offset:4096
	ds_read_b128 v[242:245], v140 offset:4096
	s_waitcnt lgkmcnt(1)
	v_mfma_f32_32x32x16_bf16 v[80:95], v[214:217], v[218:221], v[80:95]
	v_mfma_f32_32x32x16_bf16 v[16:31], v[214:217], v[230:233], v[16:31]
	ds_read_b128 v[214:217], v139 offset:6144
	ds_read_b128 v[246:249], v140 offset:6144
	s_waitcnt lgkmcnt(1)
	v_mfma_f32_32x32x16_bf16 v[64:79], v[214:217], v[218:221], v[64:79]
	v_mfma_f32_32x32x16_bf16 v[0:15], v[214:217], v[230:233], v[0:15]
	v_mfma_f32_32x32x16_bf16 v[112:127], v[226:229], v[222:225], v[112:127]
	v_mfma_f32_32x32x16_bf16 v[48:63], v[226:229], v[234:237], v[48:63]
	v_mfma_f32_32x32x16_bf16 v[96:111], v[238:241], v[222:225], v[96:111]
	v_mfma_f32_32x32x16_bf16 v[32:47], v[238:241], v[234:237], v[32:47]
	v_mfma_f32_32x32x16_bf16 v[80:95], v[242:245], v[222:225], v[80:95]
	v_mfma_f32_32x32x16_bf16 v[16:31], v[242:245], v[234:237], v[16:31]
	s_waitcnt lgkmcnt(0)
	v_mfma_f32_32x32x16_bf16 v[64:79], v[246:249], v[222:225], v[64:79]
	v_mfma_f32_32x32x16_bf16 v[0:15], v[246:249], v[234:237], v[0:15]
	s_add_u32 s5, s5, 0x6000
	s_cmp_eq_u32 s5, 0x12000
	s_cselect_b32 s5, 0, s5
	s_add_i32 s4, s4, 1
	s_cmp_lg_u32 s4, 32
	s_cbranch_scc1 .Lp2a_top
	s_barrier

.LBB0_311:
	s_and_b64 vcc, exec, s[4:5]
	s_cbranch_vccz .LBB0_218
	v_lshrrev_b32_e32 v128, 2, v204
	v_lshrrev_b32_e32 v129, 4, v204
	v_xor_b32_e32 v129, v129, v204
	v_and_b32_e32 v129, 3, v129
	v_lshlrev_b32_e32 v129, 4, v129
	v_lshl_or_b32 v128, v128, 11, v129
	v_add_u32_e32 v129, 0x20000, v128
	v_add_u32_e32 v130, 0x40000, v128
	v_add_u32_e32 v131, 0x60000, v128
	v_bfe_u32 v132, v209, 2, 2
	v_xor_b32_e32 v132, v132, v211
	v_lshlrev_b32_e32 v132, 4, v132
	v_lshl_or_b32 v132, v209, 6, v132
	v_lshl_or_b32 v133, v210, 12, v132
	v_xor_b32_e32 v134, 32, v133
	v_lshl_or_b32 v135, v212, 13, v132
	v_add_u32_e32 v135, 0x2000, v135
	v_xor_b32_e32 v136, 32, v135
	v_lshrrev_b32_e32 v137, 6, v204
	v_lshlrev_b32_e32 v137, 10, v137
	s_nop 1
	v_readfirstlane_b32 vcc_lo, v137
	s_mov_b64 s[0:1], s[78:79]
	s_mov_b64 s[6:7], s[80:81]
	s_mov_b32 s4, 0
	s_mov_b32 s5, 0
	s_mov_b32 m0, vcc_lo
	s_nop 0
	global_load_lds_dwordx4 v128, s[0:1]
	s_add_u32 m0, m0, 0x1000
	s_nop 0
	global_load_lds_dwordx4 v129, s[0:1]
	s_add_u32 m0, m0, 0x1000
	s_nop 0
	global_load_lds_dwordx4 v128, s[6:7]
	s_add_u32 m0, m0, 0x1000
	s_nop 0
	global_load_lds_dwordx4 v129, s[6:7]
	s_add_u32 m0, m0, 0x1000
	s_nop 0
	global_load_lds_dwordx4 v130, s[6:7]
	s_add_u32 m0, m0, 0x1000
	s_nop 0
	global_load_lds_dwordx4 v131, s[6:7]
	s_add_u32 s0, s0, 64
	s_addc_u32 s1, s1, 0
	s_add_u32 s6, s6, 64
	s_addc_u32 s7, s7, 0
	s_add_u32 m0, vcc_lo, 0x6000
	s_nop 0
	global_load_lds_dwordx4 v128, s[0:1]
	s_add_u32 m0, m0, 0x1000
	s_nop 0
	global_load_lds_dwordx4 v129, s[0:1]
	s_add_u32 m0, m0, 0x1000
	s_nop 0
	global_load_lds_dwordx4 v128, s[6:7]
	s_add_u32 m0, m0, 0x1000
	s_nop 0
	global_load_lds_dwordx4 v129, s[6:7]
	s_add_u32 m0, m0, 0x1000
	s_nop 0
	global_load_lds_dwordx4 v130, s[6:7]
	s_add_u32 m0, m0, 0x1000
	s_nop 0
	global_load_lds_dwordx4 v131, s[6:7]
	s_add_u32 s0, s0, 64
	s_addc_u32 s1, s1, 0
	s_add_u32 s6, s6, 64
	s_addc_u32 s7, s7, 0
	v_mov_b32_e32 v0, 0
	v_mov_b32_e32 v1, 0
	v_mov_b32_e32 v2, 0
	v_mov_b32_e32 v3, 0
	v_mov_b32_e32 v4, 0
	v_mov_b32_e32 v5, 0
	v_mov_b32_e32 v6, 0
	v_mov_b32_e32 v7, 0
	v_mov_b32_e32 v8, 0
	v_mov_b32_e32 v9, 0
	v_mov_b32_e32 v10, 0
	v_mov_b32_e32 v11, 0
	v_mov_b32_e32 v12, 0
	v_mov_b32_e32 v13, 0
	v_mov_b32_e32 v14, 0
	v_mov_b32_e32 v15, 0
	v_mov_b32_e32 v16, 0
	v_mov_b32_e32 v17, 0
	v_mov_b32_e32 v18, 0
	v_mov_b32_e32 v19, 0
	v_mov_b32_e32 v20, 0
	v_mov_b32_e32 v21, 0
	v_mov_b32_e32 v22, 0
	v_mov_b32_e32 v23, 0
	v_mov_b32_e32 v24, 0
	v_mov_b32_e32 v25, 0
	v_mov_b32_e32 v26, 0
	v_mov_b32_e32 v27, 0
	v_mov_b32_e32 v28, 0
	v_mov_b32_e32 v29, 0
	v_mov_b32_e32 v30, 0
	v_mov_b32_e32 v31, 0
	v_mov_b32_e32 v32, 0
	v_mov_b32_e32 v33, 0
	v_mov_b32_e32 v34, 0
	v_mov_b32_e32 v35, 0
	v_mov_b32_e32 v36, 0
	v_mov_b32_e32 v37, 0
	v_mov_b32_e32 v38, 0
	v_mov_b32_e32 v39, 0
	v_mov_b32_e32 v40, 0
	v_mov_b32_e32 v41, 0
	v_mov_b32_e32 v42, 0
	v_mov_b32_e32 v43, 0
	v_mov_b32_e32 v44, 0
	v_mov_b32_e32 v45, 0
	v_mov_b32_e32 v46, 0
	v_mov_b32_e32 v47, 0
	v_mov_b32_e32 v48, 0
	v_mov_b32_e32 v49, 0
	v_mov_b32_e32 v50, 0
	v_mov_b32_e32 v51, 0
	v_mov_b32_e32 v52, 0
	v_mov_b32_e32 v53, 0
	v_mov_b32_e32 v54, 0
	v_mov_b32_e32 v55, 0
	v_mov_b32_e32 v56, 0
	v_mov_b32_e32 v57, 0
	v_mov_b32_e32 v58, 0
	v_mov_b32_e32 v59, 0
	v_mov_b32_e32 v60, 0
	v_mov_b32_e32 v61, 0
	v_mov_b32_e32 v62, 0
	v_mov_b32_e32 v63, 0
	v_mov_b32_e32 v64, 0
	v_mov_b32_e32 v65, 0
	v_mov_b32_e32 v66, 0
	v_mov_b32_e32 v67, 0
	v_mov_b32_e32 v68, 0
	v_mov_b32_e32 v69, 0
	v_mov_b32_e32 v70, 0
	v_mov_b32_e32 v71, 0
	v_mov_b32_e32 v72, 0
	v_mov_b32_e32 v73, 0
	v_mov_b32_e32 v74, 0
	v_mov_b32_e32 v75, 0
	v_mov_b32_e32 v76, 0
	v_mov_b32_e32 v77, 0
	v_mov_b32_e32 v78, 0
	v_mov_b32_e32 v79, 0
	v_mov_b32_e32 v80, 0
	v_mov_b32_e32 v81, 0
	v_mov_b32_e32 v82, 0
	v_mov_b32_e32 v83, 0
	v_mov_b32_e32 v84, 0
	v_mov_b32_e32 v85, 0
	v_mov_b32_e32 v86, 0
	v_mov_b32_e32 v87, 0
	v_mov_b32_e32 v88, 0
	v_mov_b32_e32 v89, 0
	v_mov_b32_e32 v90, 0
	v_mov_b32_e32 v91, 0
	v_mov_b32_e32 v92, 0
	v_mov_b32_e32 v93, 0
	v_mov_b32_e32 v94, 0
	v_mov_b32_e32 v95, 0
	v_mov_b32_e32 v96, 0
	v_mov_b32_e32 v97, 0
	v_mov_b32_e32 v98, 0
	v_mov_b32_e32 v99, 0
	v_mov_b32_e32 v100, 0
	v_mov_b32_e32 v101, 0
	v_mov_b32_e32 v102, 0
	v_mov_b32_e32 v103, 0
	v_mov_b32_e32 v104, 0
	v_mov_b32_e32 v105, 0
	v_mov_b32_e32 v106, 0
	v_mov_b32_e32 v107, 0
	v_mov_b32_e32 v108, 0
	v_mov_b32_e32 v109, 0
	v_mov_b32_e32 v110, 0
	v_mov_b32_e32 v111, 0
	v_mov_b32_e32 v112, 0
	v_mov_b32_e32 v113, 0
	v_mov_b32_e32 v114, 0
	v_mov_b32_e32 v115, 0
	v_mov_b32_e32 v116, 0
	v_mov_b32_e32 v117, 0
	v_mov_b32_e32 v118, 0
	v_mov_b32_e32 v119, 0
	v_mov_b32_e32 v120, 0
	v_mov_b32_e32 v121, 0
	v_mov_b32_e32 v122, 0
	v_mov_b32_e32 v123, 0
	v_mov_b32_e32 v124, 0
	v_mov_b32_e32 v125, 0
	v_mov_b32_e32 v126, 0
	v_mov_b32_e32 v127, 0

.Lp2b_comp:
	v_add_u32_e32 v137, s5, v133
	v_add_u32_e32 v138, s5, v134
	v_add_u32_e32 v139, s5, v135
	v_add_u32_e32 v140, s5, v136
	ds_read_b128 v[174:177], v137
	ds_read_b128 v[214:217], v139
	ds_read_b128 v[218:221], v138
	ds_read_b128 v[222:225], v140
	ds_read_b128 v[226:229], v137 offset:2048
	ds_read_b128 v[230:233], v138 offset:2048
	s_waitcnt lgkmcnt(1)
	v_mfma_f32_32x32x16_bf16 v[48:63], v[226:229], v[214:217], v[48:63]
	v_mfma_f32_32x32x16_bf16 v[112:127], v[174:177], v[214:217], v[112:127]
	ds_read_b128 v[214:217], v139 offset:2048
	ds_read_b128 v[234:237], v140 offset:2048
	s_waitcnt lgkmcnt(1)
	v_mfma_f32_32x32x16_bf16 v[96:111], v[174:177], v[214:217], v[96:111]
	v_mfma_f32_32x32x16_bf16 v[32:47], v[226:229], v[214:217], v[32:47]
	ds_read_b128 v[214:217], v139 offset:4096
	ds_read_b128 v[238:241], v140 offset:4096
	s_waitcnt lgkmcnt(1)
	v_mfma_f32_32x32x16_bf16 v[80:95], v[174:177], v[214:217], v[80:95]
	v_mfma_f32_32x32x16_bf16 v[16:31], v[226:229], v[214:217], v[16:31]
	ds_read_b128 v[214:217], v139 offset:6144
	ds_read_b128 v[242:245], v140 offset:6144
	s_waitcnt lgkmcnt(1)
	v_mfma_f32_32x32x16_bf16 v[64:79], v[174:177], v[214:217], v[64:79]
	v_mfma_f32_32x32x16_bf16 v[0:15], v[226:229], v[214:217], v[0:15]
	v_mfma_f32_32x32x16_bf16 v[112:127], v[218:221], v[222:225], v[112:127]
	v_mfma_f32_32x32x16_bf16 v[48:63], v[230:233], v[222:225], v[48:63]
	v_mfma_f32_32x32x16_bf16 v[96:111], v[218:221], v[234:237], v[96:111]
	v_mfma_f32_32x32x16_bf16 v[32:47], v[230:233], v[234:237], v[32:47]
	v_mfma_f32_32x32x16_bf16 v[80:95], v[218:221], v[238:241], v[80:95]
	v_mfma_f32_32x32x16_bf16 v[16:31], v[230:233], v[238:241], v[16:31]
	s_waitcnt lgkmcnt(0)
	v_mfma_f32_32x32x16_bf16 v[64:79], v[218:221], v[242:245], v[64:79]
	v_mfma_f32_32x32x16_bf16 v[0:15], v[230:233], v[242:245], v[0:15]
	s_add_u32 s5, s5, 0x6000
	s_cmp_eq_u32 s5, 0x12000
	s_cselect_b32 s5, 0, s5
	s_add_i32 s4, s4, 1
	s_cmp_lg_u32 s4, 32
	s_cbranch_scc1 .Lp2b_top
	s_barrier
